# drop start-of-kernel cg grid sync; P6 epilogue ssq/sw load overlap
# baseline (speedup 1.0000x reference)
.LBB0_6:
	s_or_b64 exec, exec, s[2:3]
	v_lshrrev_b32_e32 v1, 20, v0
	v_lshrrev_b32_e32 v0, 10, v0
	v_or_b32_e32 v0, v0, v1
	s_movk_i32 s2, 0x3ff
	v_and_or_b32 v0, v0, s2, v181
	v_cmp_eq_u32_e32 vcc, 0, v0
	s_barrier
	s_and_saveexec_b64 s[2:3], vcc
	s_branch .LBB0_16

.LBB0_878:
	v_or_b32_e32 v112, 16, v168
	v_ashrrev_i32_e32 v113, 31, v112
	v_lshl_add_u64 v[114:115], v[112:113], 2, s[42:43]
	global_load_dword v130, v[114:115], off
	s_add_i32 s6, s95, 0xffff0010
	s_lshr_b32 s97, s6, 5
	s_add_i32 s6, s97, 32
	v_mov_b32_e32 v114, s6
	v_mov_b32_e32 v115, s96
	v_cmp_gt_i32_e32 vcc, s78, v112
	s_mov_b64 s[64:65], -1
	v_cndmask_b32_e32 v116, v114, v115, vcc
	v_mov_b64_e32 v[114:115], s[44:45]
	v_mad_i64_i32 v[114:115], s[6:7], v116, s91, v[114:115]
	v_lshl_add_u64 v[122:123], v[164:165], 2, v[114:115]
	global_load_dwordx4 v[114:117], v[122:123], off
	global_load_dwordx4 v[118:121], v[122:123], off offset:16
	global_load_dwordx4 v[126:129], v[122:123], off offset:128
	global_load_dwordx4 v[186:189], v[122:123], off offset:144
	s_waitcnt vmcnt(4)
	v_fmamk_f32 v130, v130, 0x3a800000, v177
	v_mul_f32_e32 v131, 0x4b800000, v130
	v_cmp_gt_f32_e64 s[6:7], s90, v130
	v_cndmask_b32_e64 v122, 0, 1, s[14:15]
	v_cmp_ne_u32_e64 s[8:9], 1, v122
	v_cndmask_b32_e64 v130, v130, v131, s[6:7]
	v_rsq_f32_e32 v130, v130
	v_cndmask_b32_e64 v123, 0, 1, s[10:11]
	v_cmp_lt_i32_e64 s[10:11], s89, v112
	s_andn2_b64 vcc, exec, s[14:15]
	v_mul_f32_e32 v122, 0x45800000, v130
	v_cndmask_b32_e64 v122, v130, v122, s[6:7]
	v_cmp_ne_u32_e64 s[6:7], 1, v123
	s_waitcnt vmcnt(0)
	v_pk_fma_f32 v[110:111], v[110:111], v[122:123], v[116:117] op_sel_hi:[1,0,1]
	v_pk_fma_f32 v[108:109], v[108:109], v[122:123], v[114:115] op_sel_hi:[1,0,1]
	v_pk_fma_f32 v[106:107], v[106:107], v[122:123], v[120:121] op_sel_hi:[1,0,1]
	v_pk_fma_f32 v[104:105], v[104:105], v[122:123], v[118:119] op_sel_hi:[1,0,1]
	v_pk_fma_f32 v[102:103], v[102:103], v[122:123], v[128:129] op_sel_hi:[1,0,1]
	v_pk_fma_f32 v[100:101], v[100:101], v[122:123], v[126:127] op_sel_hi:[1,0,1]
	v_pk_fma_f32 v[98:99], v[98:99], v[122:123], v[188:189] op_sel_hi:[1,0,1]
	v_pk_fma_f32 v[96:97], v[96:97], v[122:123], v[186:187] op_sel_hi:[1,0,1]
	s_cbranch_vccnz .LBB0_895
	s_and_b64 vcc, exec, s[6:7]
	s_mov_b64 s[14:15], -1
	s_cbranch_vccnz .LBB0_883
	s_andn2_b64 vcc, exec, s[62:63]
	s_cbranch_vccnz .LBB0_882
	v_lshlrev_b64 v[114:115], 7, v[112:113]
	v_lshl_add_u64 v[114:115], v[156:157], 0, v[114:115]
	global_store_dwordx4 v[114:115], v[108:111], off
	global_store_dwordx4 v[114:115], v[104:107], off offset:16

.LBB0_897:
	v_or_b32_e32 v96, 32, v168
	v_ashrrev_i32_e32 v97, 31, v96
	v_lshl_add_u64 v[98:99], v[96:97], 2, s[42:43]
	global_load_dword v114, v[98:99], off
	s_add_i32 s10, s95, 0xffff0020
	s_lshr_b32 s64, s10, 5
	s_add_i32 s10, s64, 32
	v_mov_b32_e32 v98, s10
	v_mov_b32_e32 v99, s96
	v_cmp_gt_i32_e32 vcc, s78, v96
	v_cndmask_b32_e32 v100, v98, v99, vcc
	v_mov_b64_e32 v[98:99], s[44:45]
	v_mad_i64_i32 v[98:99], s[10:11], v100, s91, v[98:99]
	v_lshl_add_u64 v[110:111], v[164:165], 2, v[98:99]
	global_load_dwordx4 v[98:101], v[110:111], off
	global_load_dwordx4 v[102:105], v[110:111], off offset:16
	global_load_dwordx4 v[106:109], v[110:111], off offset:128
	s_nop 0
	global_load_dwordx4 v[110:113], v[110:111], off offset:144
	s_waitcnt vmcnt(4)
	v_fmamk_f32 v114, v114, 0x3a800000, v177
	v_mul_f32_e32 v115, 0x4b800000, v114
	v_cmp_gt_f32_e64 s[14:15], s90, v114
	s_and_b64 vcc, exec, s[8:9]
	v_cmp_lt_i32_e64 s[10:11], s89, v96
	v_cndmask_b32_e64 v114, v114, v115, s[14:15]
	v_rsq_f32_e32 v114, v114
	s_nop 0
	v_mul_f32_e32 v115, 0x45800000, v114
	v_cndmask_b32_e64 v114, v114, v115, s[14:15]
	s_mov_b64 s[14:15], -1
	s_waitcnt vmcnt(0)
	v_pk_fma_f32 v[94:95], v[94:95], v[114:115], v[100:101] op_sel_hi:[1,0,1]
	v_pk_fma_f32 v[92:93], v[92:93], v[114:115], v[98:99] op_sel_hi:[1,0,1]
	v_pk_fma_f32 v[90:91], v[90:91], v[114:115], v[104:105] op_sel_hi:[1,0,1]
	v_pk_fma_f32 v[88:89], v[88:89], v[114:115], v[102:103] op_sel_hi:[1,0,1]
	v_pk_fma_f32 v[86:87], v[86:87], v[114:115], v[108:109] op_sel_hi:[1,0,1]
	v_pk_fma_f32 v[84:85], v[84:85], v[114:115], v[106:107] op_sel_hi:[1,0,1]
	v_pk_fma_f32 v[82:83], v[82:83], v[114:115], v[112:113] op_sel_hi:[1,0,1]
	v_pk_fma_f32 v[80:81], v[80:81], v[114:115], v[110:111] op_sel_hi:[1,0,1]
	s_cbranch_vccnz .LBB0_914
	s_and_b64 vcc, exec, s[6:7]
	s_cbranch_vccnz .LBB0_902
	s_andn2_b64 vcc, exec, s[62:63]
	s_cbranch_vccnz .LBB0_901
	v_lshlrev_b64 v[98:99], 7, v[96:97]
	v_lshl_add_u64 v[98:99], v[156:157], 0, v[98:99]
	global_store_dwordx4 v[98:99], v[92:95], off
	global_store_dwordx4 v[98:99], v[88:91], off offset:16

.LBB0_916:
	v_or_b32_e32 v80, 48, v168
	v_ashrrev_i32_e32 v81, 31, v80
	v_lshl_add_u64 v[82:83], v[80:81], 2, s[42:43]
	global_load_dword v98, v[82:83], off
	s_add_i32 s10, s95, 0xffff0030
	s_lshr_b32 s64, s10, 5
	s_add_i32 s10, s64, 32
	v_mov_b32_e32 v82, s10
	v_mov_b32_e32 v83, s96
	v_cmp_gt_i32_e32 vcc, s78, v80
	v_cndmask_b32_e32 v84, v82, v83, vcc
	v_mov_b64_e32 v[82:83], s[44:45]
	v_mad_i64_i32 v[82:83], s[10:11], v84, s91, v[82:83]
	v_lshl_add_u64 v[94:95], v[164:165], 2, v[82:83]
	global_load_dwordx4 v[82:85], v[94:95], off
	global_load_dwordx4 v[86:89], v[94:95], off offset:16
	global_load_dwordx4 v[90:93], v[94:95], off offset:128
	s_nop 0
	global_load_dwordx4 v[94:97], v[94:95], off offset:144
	s_waitcnt vmcnt(4)
	v_fmamk_f32 v98, v98, 0x3a800000, v177
	v_mul_f32_e32 v99, 0x4b800000, v98
	v_cmp_gt_f32_e64 s[14:15], s90, v98
	s_and_b64 vcc, exec, s[8:9]
	v_cmp_lt_i32_e64 s[10:11], s89, v80
	v_cndmask_b32_e64 v98, v98, v99, s[14:15]
	v_rsq_f32_e32 v98, v98
	s_nop 0
	v_mul_f32_e32 v99, 0x45800000, v98
	v_cndmask_b32_e64 v98, v98, v99, s[14:15]
	s_mov_b64 s[14:15], -1
	s_waitcnt vmcnt(0)
	v_pk_fma_f32 v[78:79], v[78:79], v[98:99], v[84:85] op_sel_hi:[1,0,1]
	v_pk_fma_f32 v[76:77], v[76:77], v[98:99], v[82:83] op_sel_hi:[1,0,1]
	v_pk_fma_f32 v[74:75], v[74:75], v[98:99], v[88:89] op_sel_hi:[1,0,1]
	v_pk_fma_f32 v[72:73], v[72:73], v[98:99], v[86:87] op_sel_hi:[1,0,1]
	v_pk_fma_f32 v[70:71], v[70:71], v[98:99], v[92:93] op_sel_hi:[1,0,1]
	v_pk_fma_f32 v[68:69], v[68:69], v[98:99], v[90:91] op_sel_hi:[1,0,1]
	v_pk_fma_f32 v[66:67], v[66:67], v[98:99], v[96:97] op_sel_hi:[1,0,1]
	v_pk_fma_f32 v[64:65], v[64:65], v[98:99], v[94:95] op_sel_hi:[1,0,1]
	s_cbranch_vccnz .LBB0_933
	s_and_b64 vcc, exec, s[6:7]
	s_cbranch_vccnz .LBB0_921
	s_andn2_b64 vcc, exec, s[62:63]
	s_cbranch_vccnz .LBB0_920
	v_lshlrev_b64 v[82:83], 7, v[80:81]
	v_lshl_add_u64 v[82:83], v[156:157], 0, v[82:83]
	global_store_dwordx4 v[82:83], v[76:79], off
	global_store_dwordx4 v[82:83], v[72:75], off offset:16

.LBB0_935:
	s_add_i32 s10, s95, 0x80
	v_or_b32_e32 v64, s10, v147
	v_ashrrev_i32_e32 v65, 31, v64
	v_lshl_add_u64 v[66:67], v[64:65], 2, s[42:43]
	global_load_dword v82, v[66:67], off
	s_ashr_i32 s64, s10, 11
	s_add_i32 s10, s95, 0xffff0080
	s_lshr_b32 s65, s10, 5
	s_add_i32 s10, s65, 32
	v_mov_b32_e32 v66, s10
	v_mov_b32_e32 v67, s64
	v_cmp_gt_i32_e32 vcc, s78, v64
	v_cndmask_b32_e32 v68, v66, v67, vcc
	v_mov_b64_e32 v[66:67], s[44:45]
	v_mad_i64_i32 v[66:67], s[10:11], v68, s91, v[66:67]
	v_lshl_add_u64 v[78:79], v[164:165], 2, v[66:67]
	global_load_dwordx4 v[66:69], v[78:79], off
	global_load_dwordx4 v[70:73], v[78:79], off offset:16
	global_load_dwordx4 v[74:77], v[78:79], off offset:128
	s_nop 0
	global_load_dwordx4 v[78:81], v[78:79], off offset:144
	s_waitcnt vmcnt(4)
	v_fmamk_f32 v82, v82, 0x3a800000, v177
	v_mul_f32_e32 v83, 0x4b800000, v82
	v_cmp_gt_f32_e64 s[14:15], s90, v82
	s_and_b64 vcc, exec, s[8:9]
	v_cmp_lt_i32_e64 s[10:11], s89, v64
	v_cndmask_b32_e64 v82, v82, v83, s[14:15]
	v_rsq_f32_e32 v82, v82
	s_nop 0
	v_mul_f32_e32 v83, 0x45800000, v82
	v_cndmask_b32_e64 v82, v82, v83, s[14:15]
	s_mov_b64 s[14:15], -1
	s_waitcnt vmcnt(0)
	v_pk_fma_f32 v[62:63], v[62:63], v[82:83], v[68:69] op_sel_hi:[1,0,1]
	v_pk_fma_f32 v[60:61], v[60:61], v[82:83], v[66:67] op_sel_hi:[1,0,1]
	v_pk_fma_f32 v[58:59], v[58:59], v[82:83], v[72:73] op_sel_hi:[1,0,1]
	v_pk_fma_f32 v[56:57], v[56:57], v[82:83], v[70:71] op_sel_hi:[1,0,1]
	v_pk_fma_f32 v[54:55], v[54:55], v[82:83], v[76:77] op_sel_hi:[1,0,1]
	v_pk_fma_f32 v[52:53], v[52:53], v[82:83], v[74:75] op_sel_hi:[1,0,1]
	v_pk_fma_f32 v[50:51], v[50:51], v[82:83], v[80:81] op_sel_hi:[1,0,1]
	v_pk_fma_f32 v[48:49], v[48:49], v[82:83], v[78:79] op_sel_hi:[1,0,1]
	s_cbranch_vccnz .LBB0_952
	s_and_b64 vcc, exec, s[6:7]
	s_cbranch_vccnz .LBB0_940
	s_andn2_b64 vcc, exec, s[62:63]
	s_cbranch_vccnz .LBB0_939
	v_lshlrev_b64 v[66:67], 7, v[64:65]
	v_lshl_add_u64 v[66:67], v[156:157], 0, v[66:67]
	global_store_dwordx4 v[66:67], v[60:63], off
	global_store_dwordx4 v[66:67], v[56:59], off offset:16

.LBB0_954:
	v_or_b32_e32 v48, 0x90, v147
	v_add_u32_e32 v48, s95, v48
	v_ashrrev_i32_e32 v49, 31, v48
	v_lshl_add_u64 v[50:51], v[48:49], 2, s[42:43]
	global_load_dword v66, v[50:51], off
	s_add_i32 s10, s95, 0xffff0090
	s_lshr_b32 s65, s10, 5
	s_add_i32 s10, s65, 32
	v_mov_b32_e32 v50, s10
	v_mov_b32_e32 v51, s64
	v_cmp_gt_i32_e32 vcc, s78, v48
	v_cndmask_b32_e32 v52, v50, v51, vcc
	v_mov_b64_e32 v[50:51], s[44:45]
	v_mad_i64_i32 v[50:51], s[10:11], v52, s91, v[50:51]
	v_lshl_add_u64 v[62:63], v[164:165], 2, v[50:51]
	global_load_dwordx4 v[50:53], v[62:63], off
	global_load_dwordx4 v[54:57], v[62:63], off offset:16
	global_load_dwordx4 v[58:61], v[62:63], off offset:128
	s_nop 0
	global_load_dwordx4 v[62:65], v[62:63], off offset:144
	s_waitcnt vmcnt(4)
	v_fmamk_f32 v66, v66, 0x3a800000, v177
	v_mul_f32_e32 v67, 0x4b800000, v66
	v_cmp_gt_f32_e64 s[14:15], s90, v66
	s_and_b64 vcc, exec, s[8:9]
	v_cmp_lt_i32_e64 s[10:11], s89, v48
	v_cndmask_b32_e64 v66, v66, v67, s[14:15]
	v_rsq_f32_e32 v66, v66
	s_nop 0
	v_mul_f32_e32 v67, 0x45800000, v66
	v_cndmask_b32_e64 v66, v66, v67, s[14:15]
	s_mov_b64 s[14:15], -1
	s_waitcnt vmcnt(0)
	v_pk_fma_f32 v[46:47], v[46:47], v[66:67], v[52:53] op_sel_hi:[1,0,1]
	v_pk_fma_f32 v[44:45], v[44:45], v[66:67], v[50:51] op_sel_hi:[1,0,1]
	v_pk_fma_f32 v[42:43], v[42:43], v[66:67], v[56:57] op_sel_hi:[1,0,1]
	v_pk_fma_f32 v[40:41], v[40:41], v[66:67], v[54:55] op_sel_hi:[1,0,1]
	v_pk_fma_f32 v[38:39], v[38:39], v[66:67], v[60:61] op_sel_hi:[1,0,1]
	v_pk_fma_f32 v[36:37], v[36:37], v[66:67], v[58:59] op_sel_hi:[1,0,1]
	v_pk_fma_f32 v[34:35], v[34:35], v[66:67], v[64:65] op_sel_hi:[1,0,1]
	v_pk_fma_f32 v[32:33], v[32:33], v[66:67], v[62:63] op_sel_hi:[1,0,1]
	s_cbranch_vccnz .LBB0_971
	s_and_b64 vcc, exec, s[6:7]
	s_cbranch_vccnz .LBB0_959
	s_andn2_b64 vcc, exec, s[62:63]
	s_cbranch_vccnz .LBB0_958
	v_lshlrev_b64 v[50:51], 7, v[48:49]
	v_lshl_add_u64 v[50:51], v[156:157], 0, v[50:51]
	global_store_dwordx4 v[50:51], v[44:47], off
	global_store_dwordx4 v[50:51], v[40:43], off offset:16

.LBB0_973:
	v_or_b32_e32 v32, 0xa0, v147
	v_add_u32_e32 v32, s95, v32
	v_ashrrev_i32_e32 v33, 31, v32
	v_lshl_add_u64 v[34:35], v[32:33], 2, s[42:43]
	global_load_dword v50, v[34:35], off
	s_add_i32 s10, s95, 0xffff00a0
	s_lshr_b32 s65, s10, 5
	s_add_i32 s10, s65, 32
	v_mov_b32_e32 v34, s10
	v_mov_b32_e32 v35, s64
	v_cmp_gt_i32_e32 vcc, s78, v32
	v_cndmask_b32_e32 v36, v34, v35, vcc
	v_mov_b64_e32 v[34:35], s[44:45]
	v_mad_i64_i32 v[34:35], s[10:11], v36, s91, v[34:35]
	v_lshl_add_u64 v[46:47], v[164:165], 2, v[34:35]
	global_load_dwordx4 v[34:37], v[46:47], off
	global_load_dwordx4 v[38:41], v[46:47], off offset:16
	global_load_dwordx4 v[42:45], v[46:47], off offset:128
	s_nop 0
	global_load_dwordx4 v[46:49], v[46:47], off offset:144
	s_waitcnt vmcnt(4)
	v_fmamk_f32 v50, v50, 0x3a800000, v177
	v_mul_f32_e32 v51, 0x4b800000, v50
	v_cmp_gt_f32_e64 s[14:15], s90, v50
	s_and_b64 vcc, exec, s[8:9]
	v_cmp_lt_i32_e64 s[10:11], s89, v32
	v_cndmask_b32_e64 v50, v50, v51, s[14:15]
	v_rsq_f32_e32 v50, v50
	s_nop 0
	v_mul_f32_e32 v51, 0x45800000, v50
	v_cndmask_b32_e64 v50, v50, v51, s[14:15]
	s_mov_b64 s[14:15], -1
	s_waitcnt vmcnt(0)
	v_pk_fma_f32 v[30:31], v[30:31], v[50:51], v[36:37] op_sel_hi:[1,0,1]
	v_pk_fma_f32 v[28:29], v[28:29], v[50:51], v[34:35] op_sel_hi:[1,0,1]
	v_pk_fma_f32 v[26:27], v[26:27], v[50:51], v[40:41] op_sel_hi:[1,0,1]
	v_pk_fma_f32 v[24:25], v[24:25], v[50:51], v[38:39] op_sel_hi:[1,0,1]
	v_pk_fma_f32 v[22:23], v[22:23], v[50:51], v[44:45] op_sel_hi:[1,0,1]
	v_pk_fma_f32 v[20:21], v[20:21], v[50:51], v[42:43] op_sel_hi:[1,0,1]
	v_pk_fma_f32 v[18:19], v[18:19], v[50:51], v[48:49] op_sel_hi:[1,0,1]
	v_pk_fma_f32 v[16:17], v[16:17], v[50:51], v[46:47] op_sel_hi:[1,0,1]
	s_cbranch_vccnz .LBB0_990
	s_and_b64 vcc, exec, s[6:7]
	s_cbranch_vccnz .LBB0_978
	s_andn2_b64 vcc, exec, s[62:63]
	s_cbranch_vccnz .LBB0_977
	v_lshlrev_b64 v[34:35], 7, v[32:33]
	v_lshl_add_u64 v[34:35], v[156:157], 0, v[34:35]
	global_store_dwordx4 v[34:35], v[28:31], off
	global_store_dwordx4 v[34:35], v[24:27], off offset:16

.LBB0_992:
	v_or_b32_e32 v16, 0xb0, v147
	v_add_u32_e32 v16, s95, v16
	v_ashrrev_i32_e32 v17, 31, v16
	v_lshl_add_u64 v[18:19], v[16:17], 2, s[42:43]
	global_load_dword v34, v[18:19], off
	s_add_i32 s95, s95, 0xffff00b0
	s_lshr_b32 s14, s95, 5
	s_add_i32 s10, s14, 32
	v_mov_b32_e32 v18, s10
	v_mov_b32_e32 v19, s64
	v_cmp_gt_i32_e32 vcc, s78, v16
	v_cndmask_b32_e32 v20, v18, v19, vcc
	v_mov_b64_e32 v[18:19], s[44:45]
	v_mad_i64_i32 v[18:19], s[10:11], v20, s91, v[18:19]
	v_lshl_add_u64 v[30:31], v[164:165], 2, v[18:19]
	global_load_dwordx4 v[18:21], v[30:31], off
	global_load_dwordx4 v[22:25], v[30:31], off offset:16
	global_load_dwordx4 v[26:29], v[30:31], off offset:128
	s_nop 0
	global_load_dwordx4 v[30:33], v[30:31], off offset:144
	s_waitcnt vmcnt(4)
	v_fmamk_f32 v34, v34, 0x3a800000, v177
	v_mul_f32_e32 v35, 0x4b800000, v34
	v_cmp_gt_f32_e64 s[10:11], s90, v34
	s_and_b64 vcc, exec, s[8:9]
	v_cmp_lt_i32_e64 s[8:9], s89, v16
	v_cndmask_b32_e64 v34, v34, v35, s[10:11]
	v_rsq_f32_e32 v34, v34
	s_nop 0
	v_mul_f32_e32 v35, 0x45800000, v34
	v_cndmask_b32_e64 v34, v34, v35, s[10:11]
	s_mov_b64 s[10:11], -1
	s_waitcnt vmcnt(0)
	v_pk_fma_f32 v[14:15], v[14:15], v[34:35], v[20:21] op_sel_hi:[1,0,1]
	v_pk_fma_f32 v[12:13], v[12:13], v[34:35], v[18:19] op_sel_hi:[1,0,1]
	v_pk_fma_f32 v[10:11], v[10:11], v[34:35], v[24:25] op_sel_hi:[1,0,1]
	v_pk_fma_f32 v[8:9], v[8:9], v[34:35], v[22:23] op_sel_hi:[1,0,1]
	v_pk_fma_f32 v[6:7], v[6:7], v[34:35], v[28:29] op_sel_hi:[1,0,1]
	v_pk_fma_f32 v[4:5], v[4:5], v[34:35], v[26:27] op_sel_hi:[1,0,1]
	v_pk_fma_f32 v[2:3], v[2:3], v[34:35], v[32:33] op_sel_hi:[1,0,1]
	v_pk_fma_f32 v[0:1], v[0:1], v[34:35], v[30:31] op_sel_hi:[1,0,1]
	s_cbranch_vccnz .LBB0_1009
	s_and_b64 vcc, exec, s[6:7]
	s_mov_b64 s[6:7], -1
	s_cbranch_vccnz .LBB0_997
	s_andn2_b64 vcc, exec, s[62:63]
	s_cbranch_vccnz .LBB0_996
	v_lshlrev_b64 v[18:19], 7, v[16:17]
	v_lshl_add_u64 v[18:19], v[156:157], 0, v[18:19]
	global_store_dwordx4 v[18:19], v[12:15], off
	global_store_dwordx4 v[18:19], v[8:11], off offset:16
